# stack: late queue index claim in attention items + FFN-up epilogue conv weights staged in LDS (no vmcnt waits in the epilogue) + 96 dead DPP zero-inits removed in FFN-up epilogue + MLA rope table in L
# speedup vs baseline: 1.0119x; 1.0119x over previous
.Lfu_skip7:
	s_setprio 0
	s_barrier
	s_add_u32 s8, s8, 0x40080
	s_addc_u32 s9, s9, 0
	s_add_i32 s10, s10, s43
	v_lshl_add_u64 v[66:67], s[8:9], 0, v[176:177]
	s_mov_b32 m0, s10
	s_nop 0
	global_load_lds_dwordx4 v[66:67], off
	v_lshl_add_u64 v[66:67], s[8:9], 0, v[178:179]
	s_add_i32 m0, s10, 0x2000
	s_nop 0
	global_load_lds_dwordx4 v[66:67], off
	s_waitcnt vmcnt(6)
	s_cmp_lg_u32 s40, 0
	s_cbranch_scc1 .Lcw_skip
	v_and_b32_e32 v66, 31, v163
	v_lshlrev_b32_e32 v66, 4, v66
	s_lshl_b32 s8, s13, 9
	v_add_u32_e32 v66, s8, v66
	s_mov_b64 s[10:11], exec
	s_mov_b32 exec_lo, -1
	s_mov_b32 exec_hi, 0
	s_mov_b32 m0, 0x20000
	s_nop 0
	global_load_lds_dwordx4 v66, s[26:27]
	s_mov_b32 m0, 0x20200
	s_nop 0
	global_load_lds_dwordx4 v66, s[36:37]
	s_mov_b32 m0, 0x20400
	s_nop 0
	global_load_lds_dwordx4 v66, s[38:39]
	s_mov_b32 m0, 0x20600
	s_nop 0
	global_load_lds_dwordx4 v66, s[28:29]
	s_mov_b64 exec, s[10:11]
.Lcw_skip:
	s_barrier
	s_setprio 1
	s_cmp_lg_u32 s99, 0
	s_cbranch_scc1 .Lfu_skip8
	v_mfma_f32_16x16x32_bf16 v[54:57], v[238:241], v[82:85], v[54:57]
	v_mfma_f32_16x16x32_bf16 v[46:49], v[246:249], v[82:85], v[46:49]
	v_mfma_f32_16x16x32_bf16 v[38:41], v[238:241], v[90:93], v[38:41]
	v_mfma_f32_16x16x32_bf16 v[30:33], v[246:249], v[90:93], v[30:33]
	v_mfma_f32_16x16x32_bf16 v[22:25], v[238:241], v[184:187], v[22:25]
	v_mfma_f32_16x16x32_bf16 v[18:21], v[246:249], v[184:187], v[18:21]
	v_mfma_f32_16x16x32_bf16 v[6:9], v[238:241], v[192:195], v[6:9]
	v_mfma_f32_16x16x32_bf16 v[2:5], v[246:249], v[192:195], v[2:5]
	v_mfma_f32_16x16x32_bf16 v[54:57], v[242:245], v[86:89], v[54:57]
	v_mfma_f32_16x16x32_bf16 v[46:49], v[250:253], v[86:89], v[46:49]
	v_mfma_f32_16x16x32_bf16 v[38:41], v[242:245], v[94:97], v[38:41]
	v_mfma_f32_16x16x32_bf16 v[30:33], v[250:253], v[94:97], v[30:33]
	v_mfma_f32_16x16x32_bf16 v[22:25], v[242:245], v[188:191], v[22:25]
	v_mfma_f32_16x16x32_bf16 v[18:21], v[250:253], v[188:191], v[18:21]
	v_mfma_f32_16x16x32_bf16 v[6:9], v[242:245], v[196:199], v[6:9]
	v_mfma_f32_16x16x32_bf16 v[2:5], v[250:253], v[196:199], v[2:5]
.Lfu_skip8:
	s_setprio 0
	s_add_i32 s40, s40, 2
	s_add_u32 s23, s23, 0x100
	s_addc_u32 s25, s25, 0
	s_add_u32 s6, s6, 0x100
	s_addc_u32 s7, s7, 0
	s_cmp_gt_u32 s40, 13
	s_barrier
	s_cbranch_scc0 .LBB0_56
	v_mov_b32_e32 v0, v163
	v_lshrrev_b32_e32 v66, 1, v0
	v_and_b32_e32 v66, 0x78, v66
	v_lshlrev_b32_e32 v200, 2, v66
	v_add_u32_e32 v200, 0x20000, v200
	v_lshl_or_b32 v184, s13, 7, v66
	v_ashrrev_i32_e32 v185, 31, v184
	ds_read_b128 v[66:69], v200 offset:16
	ds_read_b128 v[82:85], v200
	ds_read_b128 v[70:73], v200 offset:528
	ds_read_b128 v[86:89], v200 offset:512
	ds_read_b128 v[74:77], v200 offset:1040
	ds_read_b128 v[90:93], v200 offset:1024
	ds_read_b128 v[78:81], v200 offset:1552
	ds_read_b128 v[94:97], v200 offset:1536
	v_and_b32_e32 v230, 15, v0
	v_ashrrev_i32_e32 v0, 2, v0
	v_and_b32_e32 v0, 0xffffffc0, v0
	v_lshl_add_u32 v231, s12, 8, v0
	v_readlane_b32 s98, v254, 0
	s_and_b32 s98, s98, s99
	s_lshl_b32 s98, s98, 7
	v_add_u32_e32 v231, s98, v231
	v_mov_b32_dpp v186, v134 row_ror:15 row_mask:0xf bank_mask:0xf
	v_mov_b32_e32 v188, v1
	v_mov_b32_dpp v187, v135 row_ror:15 row_mask:0xf bank_mask:0xf
	v_mov_b32_e32 v189, v1
	v_mov_b32_dpp v194, v136 row_ror:15 row_mask:0xf bank_mask:0xf
	v_mov_b32_e32 v196, v1
	v_mov_b32_dpp v195, v137 row_ror:15 row_mask:0xf bank_mask:0xf
	v_mov_b32_e32 v197, v1
	v_mov_b32_dpp v198, v126 row_ror:15 row_mask:0xf bank_mask:0xf
	v_mov_b32_e32 v200, v1
	v_mov_b32_dpp v199, v127 row_ror:15 row_mask:0xf bank_mask:0xf
	v_mov_b32_e32 v201, v1
	v_mov_b32_dpp v190, v128 row_ror:15 row_mask:0xf bank_mask:0xf
	v_mov_b32_e32 v192, v1
	v_mov_b32_dpp v191, v129 row_ror:15 row_mask:0xf bank_mask:0xf
	v_mov_b32_e32 v193, v1
	v_or_b32_e32 v0, v231, v230
	v_mov_b32_dpp v188, v150 row_shr:1 row_mask:0xf bank_mask:0xf
	v_mov_b32_dpp v186, v150 row_shl:1 row_mask:0xf bank_mask:0xf
	v_mov_b32_dpp v189, v151 row_shr:1 row_mask:0xf bank_mask:0xf
	v_mov_b32_dpp v187, v151 row_shl:1 row_mask:0xf bank_mask:0xf
	v_mov_b32_dpp v196, v152 row_shr:1 row_mask:0xf bank_mask:0xf
	v_mov_b32_dpp v194, v152 row_shl:1 row_mask:0xf bank_mask:0xf
	v_mov_b32_dpp v197, v153 row_shr:1 row_mask:0xf bank_mask:0xf
	v_mov_b32_dpp v195, v153 row_shl:1 row_mask:0xf bank_mask:0xf
	v_mov_b32_dpp v200, v142 row_shr:1 row_mask:0xf bank_mask:0xf
	v_mov_b32_dpp v198, v142 row_shl:1 row_mask:0xf bank_mask:0xf
	v_mov_b32_dpp v201, v143 row_shr:1 row_mask:0xf bank_mask:0xf
	v_mov_b32_dpp v199, v143 row_shl:1 row_mask:0xf bank_mask:0xf
	v_mov_b32_dpp v192, v144 row_shr:1 row_mask:0xf bank_mask:0xf
	v_mov_b32_dpp v190, v144 row_shl:1 row_mask:0xf bank_mask:0xf
	v_mov_b32_dpp v193, v145 row_shr:1 row_mask:0xf bank_mask:0xf
	v_mov_b32_dpp v191, v145 row_shl:1 row_mask:0xf bank_mask:0xf
	v_cmp_eq_u32_e64 s[6:7], 0, v230
	v_cmp_ne_u32_e64 s[10:11], 0, v230
	s_and_saveexec_b64 s[8:9], s[10:11]
	s_cbranch_execz .LBB0_59
	s_waitcnt lgkmcnt(0)
	v_pk_fma_f32 v[200:201], v[66:67], v[200:201], v[78:79]
	v_pk_fma_f32 v[196:197], v[84:85], v[196:197], v[96:97]
	v_pk_fma_f32 v[200:201], v[142:143], v[70:71], v[200:201]
	v_pk_fma_f32 v[196:197], v[152:153], v[88:89], v[196:197]
	v_pk_fma_f32 v[198:199], v[74:75], v[198:199], v[200:201]
	v_pk_fma_f32 v[194:195], v[92:93], v[194:195], v[196:197]
	v_mul_f32_e32 v172, 0xbfb8aa3b, v198
	v_exp_f32_e32 v172, v172
	v_mul_f32_e32 v173, 0xbfb8aa3b, v199
	v_exp_f32_e32 v173, v173
	v_pk_fma_f32 v[188:189], v[82:83], v[188:189], v[94:95]
	v_add_f32_e32 v172, 1.0, v172
	v_rcp_f32_e32 v200, v172
	v_add_f32_e32 v173, 1.0, v173
	v_mul_f32_e32 v172, 0xbfb8aa3b, v194
	v_rcp_f32_e32 v201, v173
	v_exp_f32_e32 v172, v172
	v_mul_f32_e32 v173, 0xbfb8aa3b, v195
	v_exp_f32_e32 v173, v173
	v_pk_mul_f32 v[198:199], v[198:199], v[200:201]
	v_add_f32_e32 v172, 1.0, v172
	v_pk_fma_f32 v[188:189], v[150:151], v[86:87], v[188:189]
	v_pk_mul_f32 v[196:197], v[154:155], v[198:199]
	v_rcp_f32_e32 v198, v172
	v_add_f32_e32 v172, 1.0, v173
	v_pk_fma_f32 v[186:187], v[90:91], v[186:187], v[188:189]
	v_rcp_f32_e32 v199, v172
	v_mul_f32_e32 v172, 0xbfb8aa3b, v186
	v_exp_f32_e32 v172, v172
	v_mul_f32_e32 v173, 0xbfb8aa3b, v187
	v_exp_f32_e32 v173, v173
	v_pk_fma_f32 v[192:193], v[68:69], v[192:193], v[80:81]
	v_add_f32_e32 v172, 1.0, v172
	v_pk_fma_f32 v[192:193], v[144:145], v[72:73], v[192:193]
	v_pk_mul_f32 v[188:189], v[194:195], v[198:199]
	v_pk_fma_f32 v[190:191], v[76:77], v[190:191], v[192:193]
	v_rcp_f32_e32 v194, v172
	v_add_f32_e32 v172, 1.0, v173
	v_mul_f32_e32 v173, 0xbfb8aa3b, v190
	v_exp_f32_e32 v173, v173
	v_mul_f32_e32 v174, 0xbfb8aa3b, v191
	v_exp_f32_e32 v174, v174
	v_rcp_f32_e32 v195, v172
	v_add_f32_e32 v172, 1.0, v173
	v_rcp_f32_e32 v192, v172
	v_add_f32_e32 v172, 1.0, v174
	v_rcp_f32_e32 v193, v172
	v_readlane_b32 s12, v254, 35
	v_readlane_b32 s13, v254, 36
	v_pk_mul_f32 v[186:187], v[186:187], v[194:195]
	v_pk_mul_f32 v[190:191], v[190:191], v[192:193]
	v_mov_b64_e32 v[192:193], s[12:13]
	s_movk_i32 s12, 0x1600
	v_pk_mul_f32 v[188:189], v[160:161], v[188:189]
	v_pk_mul_f32 v[186:187], v[158:159], v[186:187]
	v_pk_mul_f32 v[190:191], v[156:157], v[190:191]
	v_mad_i64_i32 v[192:193], s[12:13], v0, s12, v[192:193]
	v_lshl_add_u64 v[192:193], v[184:185], 1, v[192:193]
	v_cvt_pk_bf16_f32 v186, v186, v187
	v_cvt_pk_bf16_f32 v187, v188, v189
	v_cvt_pk_bf16_f32 v188, v196, v197
	v_cvt_pk_bf16_f32 v189, v190, v191
	global_store_dwordx4 v[192:193], v[186:189], off

.LBB0_62:
	s_or_b64 exec, exec, s[8:9]
	s_nop 0
	v_readlane_b32 s8, v254, 35
	v_mov_b32_dpp v154, v150 row_ror:1 row_mask:0xf bank_mask:0xf
	v_mov_b32_dpp v155, v151 row_ror:1 row_mask:0xf bank_mask:0xf
	v_mov_b32_dpp v154, v134 row_shr:1 row_mask:0xf bank_mask:0xf
	v_mov_b32_dpp v155, v135 row_shr:1 row_mask:0xf bank_mask:0xf
	v_mov_b32_dpp v150, v118 row_ror:15 row_mask:0xf bank_mask:0xf
	v_mov_b32_dpp v151, v119 row_ror:15 row_mask:0xf bank_mask:0xf
	s_waitcnt lgkmcnt(0)
	v_pk_fma_f32 v[154:155], v[82:83], v[154:155], v[94:95]
	v_mov_b32_dpp v150, v134 row_shl:1 row_mask:0xf bank_mask:0xf
	v_mov_b32_dpp v151, v135 row_shl:1 row_mask:0xf bank_mask:0xf
	v_pk_fma_f32 v[154:155], v[134:135], v[86:87], v[154:155]
	v_readlane_b32 s9, v254, 36
	v_pk_fma_f32 v[150:151], v[90:91], v[150:151], v[154:155]
	v_or_b32_e32 v156, 16, v0
	v_mul_f32_e32 v154, 0xbfb8aa3b, v150
	v_mul_f32_e32 v155, 0xbfb8aa3b, v151
	v_exp_f32_e32 v154, v154
	v_exp_f32_e32 v155, v155
	s_movk_i32 s14, 0x1600
	s_movk_i32 s25, 0x1600
	v_add_f32_e32 v154, 1.0, v154
	v_add_f32_e32 v155, 1.0, v155
	v_rcp_f32_e32 v154, v154
	v_rcp_f32_e32 v155, v155
	s_nop 0
	v_pk_mul_f32 v[150:151], v[150:151], v[154:155]
	s_nop 0
	v_pk_mul_f32 v[146:147], v[146:147], v[150:151]
	s_nop 0
	v_mov_b32_dpp v150, v152 row_ror:1 row_mask:0xf bank_mask:0xf
	v_mov_b32_dpp v151, v153 row_ror:1 row_mask:0xf bank_mask:0xf
	v_mov_b32_dpp v150, v136 row_shr:1 row_mask:0xf bank_mask:0xf
	v_mov_b32_dpp v151, v137 row_shr:1 row_mask:0xf bank_mask:0xf
	v_mov_b32_dpp v152, v120 row_ror:15 row_mask:0xf bank_mask:0xf
	v_mov_b32_dpp v153, v121 row_ror:15 row_mask:0xf bank_mask:0xf
	v_pk_fma_f32 v[150:151], v[84:85], v[150:151], v[96:97]
	v_mov_b32_dpp v152, v136 row_shl:1 row_mask:0xf bank_mask:0xf
	v_mov_b32_dpp v153, v137 row_shl:1 row_mask:0xf bank_mask:0xf
	v_pk_fma_f32 v[150:151], v[136:137], v[88:89], v[150:151]
	s_nop 0
	v_pk_fma_f32 v[150:151], v[92:93], v[152:153], v[150:151]
	s_nop 0
	v_mul_f32_e32 v152, 0xbfb8aa3b, v150
	v_mul_f32_e32 v153, 0xbfb8aa3b, v151
	v_exp_f32_e32 v152, v152
	v_exp_f32_e32 v153, v153
	v_add_f32_e32 v152, 1.0, v152
	v_add_f32_e32 v153, 1.0, v153
	v_rcp_f32_e32 v152, v152
	v_rcp_f32_e32 v153, v153
	s_nop 0
	v_pk_mul_f32 v[150:151], v[150:151], v[152:153]
	s_nop 0
	v_pk_mul_f32 v[148:149], v[148:149], v[150:151]
	s_nop 0
	v_mov_b32_dpp v150, v142 row_ror:1 row_mask:0xf bank_mask:0xf
	v_mov_b32_dpp v151, v143 row_ror:1 row_mask:0xf bank_mask:0xf
	v_mov_b32_dpp v150, v126 row_shr:1 row_mask:0xf bank_mask:0xf
	v_mov_b32_dpp v151, v127 row_shr:1 row_mask:0xf bank_mask:0xf
	v_mov_b32_dpp v142, v114 row_ror:15 row_mask:0xf bank_mask:0xf
	v_mov_b32_dpp v143, v115 row_ror:15 row_mask:0xf bank_mask:0xf
	v_pk_fma_f32 v[150:151], v[66:67], v[150:151], v[78:79]
	v_mov_b32_dpp v142, v126 row_shl:1 row_mask:0xf bank_mask:0xf
	v_mov_b32_dpp v143, v127 row_shl:1 row_mask:0xf bank_mask:0xf
	v_pk_fma_f32 v[150:151], v[126:127], v[70:71], v[150:151]
	s_nop 0
	v_pk_fma_f32 v[142:143], v[74:75], v[142:143], v[150:151]
	s_nop 0
	v_mul_f32_e32 v150, 0xbfb8aa3b, v142
	v_mul_f32_e32 v151, 0xbfb8aa3b, v143
	v_exp_f32_e32 v150, v150
	v_exp_f32_e32 v151, v151
	v_add_f32_e32 v150, 1.0, v150
	v_add_f32_e32 v151, 1.0, v151
	v_rcp_f32_e32 v150, v150
	v_rcp_f32_e32 v151, v151
	s_nop 0
	v_pk_mul_f32 v[142:143], v[142:143], v[150:151]
	s_nop 0
	v_pk_mul_f32 v[150:151], v[138:139], v[142:143]
	v_mov_b32_dpp v138, v144 row_ror:1 row_mask:0xf bank_mask:0xf
	v_mov_b32_dpp v139, v145 row_ror:1 row_mask:0xf bank_mask:0xf
	v_mov_b32_dpp v138, v128 row_shr:1 row_mask:0xf bank_mask:0xf
	v_mov_b32_dpp v139, v129 row_shr:1 row_mask:0xf bank_mask:0xf
	v_mov_b32_dpp v142, v116 row_ror:15 row_mask:0xf bank_mask:0xf
	v_mov_b32_dpp v143, v117 row_ror:15 row_mask:0xf bank_mask:0xf
	v_pk_fma_f32 v[138:139], v[68:69], v[138:139], v[80:81]
	v_mov_b32_dpp v142, v128 row_shl:1 row_mask:0xf bank_mask:0xf
	v_mov_b32_dpp v143, v129 row_shl:1 row_mask:0xf bank_mask:0xf
	v_pk_fma_f32 v[138:139], v[128:129], v[72:73], v[138:139]
	v_cvt_pk_bf16_f32 v144, v150, v151
	v_pk_fma_f32 v[138:139], v[76:77], v[142:143], v[138:139]
	s_nop 0
	v_mul_f32_e32 v142, 0xbfb8aa3b, v138
	v_mul_f32_e32 v143, 0xbfb8aa3b, v139
	v_exp_f32_e32 v142, v142
	v_exp_f32_e32 v143, v143
	v_add_f32_e32 v142, 1.0, v142
	v_add_f32_e32 v143, 1.0, v143
	v_rcp_f32_e32 v142, v142
	v_rcp_f32_e32 v143, v143
	s_nop 0
	v_pk_mul_f32 v[138:139], v[138:139], v[142:143]
	s_nop 0
	v_pk_mul_f32 v[152:153], v[140:141], v[138:139]
	v_mov_b64_e32 v[140:141], s[8:9]
	v_mad_i64_i32 v[142:143], s[8:9], v156, s14, v[140:141]
	v_lshlrev_b64 v[138:139], 1, v[184:185]
	v_lshl_add_u64 v[154:155], v[142:143], 0, v[138:139]
	v_cvt_pk_bf16_f32 v142, v146, v147
	v_cvt_pk_bf16_f32 v143, v148, v149
	v_cvt_pk_bf16_f32 v145, v152, v153
	global_store_dwordx4 v[154:155], v[142:145], off
	s_nop 1
	v_or_b32_e32 v144, 32, v0
	v_mov_b32_dpp v142, v134 row_ror:1 row_mask:0xf bank_mask:0xf
	v_mov_b32_dpp v143, v135 row_ror:1 row_mask:0xf bank_mask:0xf
	v_mov_b32_dpp v142, v118 row_shr:1 row_mask:0xf bank_mask:0xf
	v_mov_b32_dpp v143, v119 row_shr:1 row_mask:0xf bank_mask:0xf
	v_mov_b32_dpp v134, v102 row_ror:15 row_mask:0xf bank_mask:0xf
	v_mov_b32_dpp v135, v103 row_ror:15 row_mask:0xf bank_mask:0xf
	v_pk_fma_f32 v[142:143], v[82:83], v[142:143], v[94:95]
	v_mov_b32_dpp v134, v118 row_shl:1 row_mask:0xf bank_mask:0xf
	v_mov_b32_dpp v135, v119 row_shl:1 row_mask:0xf bank_mask:0xf
	v_pk_fma_f32 v[142:143], v[118:119], v[86:87], v[142:143]
	s_nop 0
	v_pk_fma_f32 v[134:135], v[90:91], v[134:135], v[142:143]
	s_nop 0
	v_mul_f32_e32 v142, 0xbfb8aa3b, v134
	v_mul_f32_e32 v143, 0xbfb8aa3b, v135
	v_exp_f32_e32 v142, v142
	v_exp_f32_e32 v143, v143
	v_add_f32_e32 v142, 1.0, v142
	v_add_f32_e32 v143, 1.0, v143
	v_rcp_f32_e32 v142, v142
	v_rcp_f32_e32 v143, v143
	s_nop 0
	v_pk_mul_f32 v[134:135], v[134:135], v[142:143]
	s_nop 0
	v_pk_mul_f32 v[130:131], v[130:131], v[134:135]
	s_nop 0
	v_mov_b32_dpp v134, v136 row_ror:1 row_mask:0xf bank_mask:0xf
	v_mov_b32_dpp v135, v137 row_ror:1 row_mask:0xf bank_mask:0xf
	v_mov_b32_dpp v134, v120 row_shr:1 row_mask:0xf bank_mask:0xf
	v_mov_b32_dpp v135, v121 row_shr:1 row_mask:0xf bank_mask:0xf
	v_mov_b32_dpp v136, v104 row_ror:15 row_mask:0xf bank_mask:0xf
	v_mov_b32_dpp v137, v105 row_ror:15 row_mask:0xf bank_mask:0xf
	v_pk_fma_f32 v[134:135], v[84:85], v[134:135], v[96:97]
	v_mov_b32_dpp v136, v120 row_shl:1 row_mask:0xf bank_mask:0xf
	v_mov_b32_dpp v137, v121 row_shl:1 row_mask:0xf bank_mask:0xf
	v_pk_fma_f32 v[134:135], v[120:121], v[88:89], v[134:135]
	s_nop 0
	v_pk_fma_f32 v[134:135], v[92:93], v[136:137], v[134:135]
	s_nop 0
	v_mul_f32_e32 v136, 0xbfb8aa3b, v134
	v_mul_f32_e32 v137, 0xbfb8aa3b, v135
	v_exp_f32_e32 v136, v136
	v_exp_f32_e32 v137, v137
	v_add_f32_e32 v136, 1.0, v136
	v_add_f32_e32 v137, 1.0, v137
	v_rcp_f32_e32 v136, v136
	v_rcp_f32_e32 v137, v137
	s_nop 0
	v_pk_mul_f32 v[134:135], v[134:135], v[136:137]
	s_nop 0
	v_pk_mul_f32 v[132:133], v[132:133], v[134:135]
	s_nop 0
	v_mov_b32_dpp v134, v126 row_ror:1 row_mask:0xf bank_mask:0xf
	v_mov_b32_dpp v135, v127 row_ror:1 row_mask:0xf bank_mask:0xf
	v_mov_b32_dpp v134, v114 row_shr:1 row_mask:0xf bank_mask:0xf
	v_mov_b32_dpp v135, v115 row_shr:1 row_mask:0xf bank_mask:0xf
	v_mov_b32_dpp v126, v98 row_ror:15 row_mask:0xf bank_mask:0xf
	v_mov_b32_dpp v127, v99 row_ror:15 row_mask:0xf bank_mask:0xf
	v_pk_fma_f32 v[134:135], v[66:67], v[134:135], v[78:79]
	v_mov_b32_dpp v126, v114 row_shl:1 row_mask:0xf bank_mask:0xf
	v_mov_b32_dpp v127, v115 row_shl:1 row_mask:0xf bank_mask:0xf
	v_pk_fma_f32 v[134:135], v[114:115], v[70:71], v[134:135]
	s_nop 0
	v_pk_fma_f32 v[126:127], v[74:75], v[126:127], v[134:135]
	s_nop 0
	v_mul_f32_e32 v134, 0xbfb8aa3b, v126
	v_mul_f32_e32 v135, 0xbfb8aa3b, v127
	v_exp_f32_e32 v134, v134
	v_exp_f32_e32 v135, v135
	v_add_f32_e32 v134, 1.0, v134
	v_add_f32_e32 v135, 1.0, v135
	v_rcp_f32_e32 v134, v134
	v_rcp_f32_e32 v135, v135
	s_nop 0
	v_pk_mul_f32 v[126:127], v[126:127], v[134:135]
	s_nop 0
	v_pk_mul_f32 v[126:127], v[122:123], v[126:127]
	s_nop 0
	v_mov_b32_dpp v122, v128 row_ror:1 row_mask:0xf bank_mask:0xf
	v_mov_b32_dpp v123, v129 row_ror:1 row_mask:0xf bank_mask:0xf
	v_mov_b32_dpp v122, v116 row_shr:1 row_mask:0xf bank_mask:0xf
	v_mov_b32_dpp v123, v117 row_shr:1 row_mask:0xf bank_mask:0xf
	v_mov_b32_dpp v128, v100 row_ror:15 row_mask:0xf bank_mask:0xf
	v_mov_b32_dpp v129, v101 row_ror:15 row_mask:0xf bank_mask:0xf
	v_pk_fma_f32 v[122:123], v[68:69], v[122:123], v[80:81]
	v_mov_b32_dpp v128, v116 row_shl:1 row_mask:0xf bank_mask:0xf
	v_mov_b32_dpp v129, v117 row_shl:1 row_mask:0xf bank_mask:0xf
	v_pk_fma_f32 v[122:123], v[116:117], v[72:73], v[122:123]
	s_nop 0
	v_pk_fma_f32 v[122:123], v[76:77], v[128:129], v[122:123]
	s_nop 0
	v_mul_f32_e32 v128, 0xbfb8aa3b, v122
	v_mul_f32_e32 v129, 0xbfb8aa3b, v123
	v_exp_f32_e32 v128, v128
	v_exp_f32_e32 v129, v129
	v_add_f32_e32 v128, 1.0, v128
	v_add_f32_e32 v129, 1.0, v129
	v_rcp_f32_e32 v128, v128
	v_rcp_f32_e32 v129, v129
	s_nop 0
	v_pk_mul_f32 v[122:123], v[122:123], v[128:129]
	s_nop 0
	v_pk_mul_f32 v[128:129], v[124:125], v[122:123]
	v_mad_i64_i32 v[122:123], s[8:9], v144, s14, v[140:141]
	v_lshl_add_u64 v[134:135], v[122:123], 0, v[138:139]
	v_cvt_pk_bf16_f32 v122, v130, v131
	v_cvt_pk_bf16_f32 v123, v132, v133
	v_cvt_pk_bf16_f32 v124, v126, v127
	v_cvt_pk_bf16_f32 v125, v128, v129
	global_store_dwordx4 v[134:135], v[122:125], off
	v_mov_b32_dpp v126, v114 row_ror:1 row_mask:0xf bank_mask:0xf
	v_mov_b32_dpp v127, v115 row_ror:1 row_mask:0xf bank_mask:0xf
	v_mov_b32_dpp v122, v118 row_ror:1 row_mask:0xf bank_mask:0xf
	v_mov_b32_e32 v118, v1
	v_mov_b32_dpp v123, v119 row_ror:1 row_mask:0xf bank_mask:0xf
	v_mov_b32_e32 v119, v1
	v_mov_b32_dpp v124, v120 row_ror:1 row_mask:0xf bank_mask:0xf
	v_mov_b32_e32 v120, v1
	v_mov_b32_dpp v125, v121 row_ror:1 row_mask:0xf bank_mask:0xf
	v_mov_b32_e32 v121, v1
	v_mov_b32_e32 v128, v1
	v_mov_b32_e32 v129, v1
	v_mov_b32_dpp v114, v116 row_ror:1 row_mask:0xf bank_mask:0xf
	v_mov_b32_e32 v116, v1
	v_mov_b32_dpp v115, v117 row_ror:1 row_mask:0xf bank_mask:0xf
	v_mov_b32_e32 v117, v1
	v_mov_b32_dpp v122, v102 row_shr:1 row_mask:0xf bank_mask:0xf
	v_mov_b32_dpp v118, v102 row_shl:1 row_mask:0xf bank_mask:0xf
	v_mov_b32_dpp v123, v103 row_shr:1 row_mask:0xf bank_mask:0xf
	v_mov_b32_dpp v119, v103 row_shl:1 row_mask:0xf bank_mask:0xf
	v_mov_b32_dpp v124, v104 row_shr:1 row_mask:0xf bank_mask:0xf
	v_mov_b32_dpp v120, v104 row_shl:1 row_mask:0xf bank_mask:0xf
	v_mov_b32_dpp v125, v105 row_shr:1 row_mask:0xf bank_mask:0xf
	v_mov_b32_dpp v121, v105 row_shl:1 row_mask:0xf bank_mask:0xf
	v_mov_b32_dpp v126, v98 row_shr:1 row_mask:0xf bank_mask:0xf
	v_mov_b32_dpp v128, v98 row_shl:1 row_mask:0xf bank_mask:0xf
	v_mov_b32_dpp v127, v99 row_shr:1 row_mask:0xf bank_mask:0xf
	v_mov_b32_dpp v129, v99 row_shl:1 row_mask:0xf bank_mask:0xf
	v_mov_b32_dpp v114, v100 row_shr:1 row_mask:0xf bank_mask:0xf
	v_mov_b32_dpp v116, v100 row_shl:1 row_mask:0xf bank_mask:0xf
	v_mov_b32_dpp v115, v101 row_shr:1 row_mask:0xf bank_mask:0xf
	v_mov_b32_dpp v117, v101 row_shl:1 row_mask:0xf bank_mask:0xf
	v_cmp_eq_u32_e64 s[8:9], 15, v230
	v_cmp_ne_u32_e64 s[14:15], 15, v230
	s_and_saveexec_b64 s[16:17], s[14:15]
	s_cbranch_execz .LBB0_64
	v_pk_fma_f32 v[114:115], v[68:69], v[114:115], v[80:81]
	v_pk_fma_f32 v[126:127], v[66:67], v[126:127], v[78:79]
	v_pk_fma_f32 v[124:125], v[84:85], v[124:125], v[96:97]
	v_pk_fma_f32 v[122:123], v[82:83], v[122:123], v[94:95]
	v_pk_fma_f32 v[114:115], v[100:101], v[72:73], v[114:115]
	v_pk_fma_f32 v[126:127], v[98:99], v[70:71], v[126:127]
	v_pk_fma_f32 v[124:125], v[104:105], v[88:89], v[124:125]
	v_pk_fma_f32 v[122:123], v[102:103], v[86:87], v[122:123]
	v_pk_fma_f32 v[114:115], v[76:77], v[116:117], v[114:115]
	v_pk_fma_f32 v[126:127], v[74:75], v[128:129], v[126:127]
	v_pk_fma_f32 v[120:121], v[92:93], v[120:121], v[124:125]
	v_pk_fma_f32 v[118:119], v[90:91], v[118:119], v[122:123]
	v_mul_f32_e32 v116, 0xbfb8aa3b, v114
	v_mul_f32_e32 v117, 0xbfb8aa3b, v115
	v_mul_f32_e32 v128, 0xbfb8aa3b, v126
	v_mul_f32_e32 v129, 0xbfb8aa3b, v127
	v_mul_f32_e32 v124, 0xbfb8aa3b, v120
	v_mul_f32_e32 v125, 0xbfb8aa3b, v121
	v_mul_f32_e32 v122, 0xbfb8aa3b, v118
	v_mul_f32_e32 v123, 0xbfb8aa3b, v119
	v_exp_f32_e32 v116, v116
	v_exp_f32_e32 v117, v117
	v_exp_f32_e32 v128, v128
	v_exp_f32_e32 v129, v129
	v_exp_f32_e32 v124, v124
	v_exp_f32_e32 v125, v125
	v_exp_f32_e32 v122, v122
	v_exp_f32_e32 v123, v123
	v_add_f32_e32 v116, 1.0, v116
	v_add_f32_e32 v117, 1.0, v117
	v_add_f32_e32 v128, 1.0, v128
	v_add_f32_e32 v129, 1.0, v129
	v_add_f32_e32 v124, 1.0, v124
	v_add_f32_e32 v125, 1.0, v125
	v_add_f32_e32 v122, 1.0, v122
	v_add_f32_e32 v123, 1.0, v123
	v_rcp_f32_e32 v116, v116
	v_rcp_f32_e32 v117, v117
	v_rcp_f32_e32 v128, v128
	v_rcp_f32_e32 v129, v129
	v_rcp_f32_e32 v124, v124
	v_rcp_f32_e32 v125, v125
	v_rcp_f32_e32 v122, v122
	v_rcp_f32_e32 v123, v123
	v_readlane_b32 s40, v254, 35
	v_pk_mul_f32 v[114:115], v[114:115], v[116:117]
	v_readlane_b32 s41, v254, 36
	v_pk_mul_f32 v[126:127], v[126:127], v[128:129]
	v_pk_mul_f32 v[120:121], v[120:121], v[124:125]
	v_pk_mul_f32 v[118:119], v[118:119], v[122:123]
	v_or_b32_e32 v0, 48, v0
	v_pk_mul_f32 v[122:123], v[108:109], v[114:115]
	v_mov_b64_e32 v[114:115], s[40:41]
	v_pk_mul_f32 v[126:127], v[106:107], v[126:127]
	v_pk_mul_f32 v[120:121], v[112:113], v[120:121]
	v_pk_mul_f32 v[118:119], v[110:111], v[118:119]
	v_mad_i64_i32 v[114:115], s[40:41], v0, s25, v[114:115]
	v_lshl_add_u64 v[124:125], v[184:185], 1, v[114:115]
	v_cvt_pk_bf16_f32 v114, v118, v119
	v_cvt_pk_bf16_f32 v115, v120, v121
	v_cvt_pk_bf16_f32 v116, v126, v127
	v_cvt_pk_bf16_f32 v117, v122, v123
	global_store_dwordx4 v[124:125], v[114:117], off

.LBB0_67:
	s_or_b64 exec, exec, s[40:41]
	s_cmp_lg_u32 s99, 0
	s_cbranch_scc1 .LBB0_52
	v_add_u32_e32 v115, 0x80, v231
	v_mov_b32_dpp v98, v38 row_ror:15 row_mask:0xf bank_mask:0xf
	v_mov_b32_e32 v100, v1
	v_mov_b32_dpp v99, v39 row_ror:15 row_mask:0xf bank_mask:0xf
	v_mov_b32_e32 v101, v1
	v_mov_b32_dpp v106, v40 row_ror:15 row_mask:0xf bank_mask:0xf
	v_mov_b32_e32 v108, v1
	v_mov_b32_dpp v107, v41 row_ror:15 row_mask:0xf bank_mask:0xf
	v_mov_b32_e32 v109, v1
	v_mov_b32_dpp v110, v30 row_ror:15 row_mask:0xf bank_mask:0xf
	v_mov_b32_e32 v112, v1
	v_mov_b32_dpp v111, v31 row_ror:15 row_mask:0xf bank_mask:0xf
	v_mov_b32_e32 v113, v1
	v_mov_b32_dpp v102, v32 row_ror:15 row_mask:0xf bank_mask:0xf
	v_mov_b32_e32 v104, v1
	v_mov_b32_dpp v103, v33 row_ror:15 row_mask:0xf bank_mask:0xf
	v_mov_b32_e32 v105, v1
	v_or_b32_e32 v114, v115, v230
	v_mov_b32_dpp v100, v54 row_shr:1 row_mask:0xf bank_mask:0xf
	v_mov_b32_dpp v98, v54 row_shl:1 row_mask:0xf bank_mask:0xf
	v_mov_b32_dpp v101, v55 row_shr:1 row_mask:0xf bank_mask:0xf
	v_mov_b32_dpp v99, v55 row_shl:1 row_mask:0xf bank_mask:0xf
	v_mov_b32_dpp v108, v56 row_shr:1 row_mask:0xf bank_mask:0xf
	v_mov_b32_dpp v106, v56 row_shl:1 row_mask:0xf bank_mask:0xf
	v_mov_b32_dpp v109, v57 row_shr:1 row_mask:0xf bank_mask:0xf
	v_mov_b32_dpp v107, v57 row_shl:1 row_mask:0xf bank_mask:0xf
	v_mov_b32_dpp v112, v46 row_shr:1 row_mask:0xf bank_mask:0xf
	v_mov_b32_dpp v110, v46 row_shl:1 row_mask:0xf bank_mask:0xf
	v_mov_b32_dpp v113, v47 row_shr:1 row_mask:0xf bank_mask:0xf
	v_mov_b32_dpp v111, v47 row_shl:1 row_mask:0xf bank_mask:0xf
	v_mov_b32_dpp v104, v48 row_shr:1 row_mask:0xf bank_mask:0xf
	v_mov_b32_dpp v102, v48 row_shl:1 row_mask:0xf bank_mask:0xf
	v_mov_b32_dpp v105, v49 row_shr:1 row_mask:0xf bank_mask:0xf
	v_mov_b32_dpp v103, v49 row_shl:1 row_mask:0xf bank_mask:0xf
	s_and_saveexec_b64 s[40:41], s[10:11]
	s_cbranch_execz .LBB0_69
	v_pk_fma_f32 v[112:113], v[66:67], v[112:113], v[78:79]
	v_pk_fma_f32 v[108:109], v[84:85], v[108:109], v[96:97]
	v_pk_fma_f32 v[112:113], v[46:47], v[70:71], v[112:113]
	v_pk_fma_f32 v[108:109], v[56:57], v[88:89], v[108:109]
	v_pk_fma_f32 v[110:111], v[74:75], v[110:111], v[112:113]
	v_pk_fma_f32 v[106:107], v[92:93], v[106:107], v[108:109]
	v_mul_f32_e32 v112, 0xbfb8aa3b, v110
	v_mul_f32_e32 v113, 0xbfb8aa3b, v111
	v_exp_f32_e32 v112, v112
	v_exp_f32_e32 v113, v113
	v_mul_f32_e32 v108, 0xbfb8aa3b, v106
	v_pk_fma_f32 v[100:101], v[82:83], v[100:101], v[94:95]
	v_add_f32_e32 v112, 1.0, v112
	v_add_f32_e32 v113, 1.0, v113
	v_rcp_f32_e32 v112, v112
	v_rcp_f32_e32 v113, v113
	v_pk_fma_f32 v[100:101], v[54:55], v[86:87], v[100:101]
	v_pk_fma_f32 v[104:105], v[68:69], v[104:105], v[80:81]
	v_pk_fma_f32 v[98:99], v[90:91], v[98:99], v[100:101]
	v_pk_mul_f32 v[110:111], v[110:111], v[112:113]
	v_exp_f32_e32 v112, v108
	v_mul_f32_e32 v108, 0xbfb8aa3b, v107
	v_exp_f32_e32 v113, v108
	v_pk_fma_f32 v[104:105], v[48:49], v[72:73], v[104:105]
	v_mul_f32_e32 v100, 0xbfb8aa3b, v98
	v_pk_fma_f32 v[102:103], v[76:77], v[102:103], v[104:105]
	v_pk_mul_f32 v[108:109], v[58:59], v[110:111]
	v_add_f32_e32 v110, 1.0, v112
	v_add_f32_e32 v111, 1.0, v113
	v_exp_f32_e32 v112, v100
	v_mul_f32_e32 v100, 0xbfb8aa3b, v99
	v_mul_f32_e32 v104, 0xbfb8aa3b, v102
	v_mul_f32_e32 v105, 0xbfb8aa3b, v103
	v_rcp_f32_e32 v110, v110
	v_rcp_f32_e32 v111, v111
	v_exp_f32_e32 v113, v100
	v_exp_f32_e32 v104, v104
	v_exp_f32_e32 v105, v105
	v_pk_mul_f32 v[100:101], v[106:107], v[110:111]
	v_add_f32_e32 v106, 1.0, v112
	v_add_f32_e32 v107, 1.0, v113
	v_add_f32_e32 v104, 1.0, v104
	v_add_f32_e32 v105, 1.0, v105
	v_rcp_f32_e32 v106, v106
	v_rcp_f32_e32 v107, v107
	v_rcp_f32_e32 v104, v104
	v_rcp_f32_e32 v105, v105
	v_readlane_b32 s10, v254, 35
	v_readlane_b32 s11, v254, 36
	v_pk_mul_f32 v[98:99], v[98:99], v[106:107]
	v_pk_mul_f32 v[102:103], v[102:103], v[104:105]
	v_mov_b64_e32 v[104:105], s[10:11]
	v_pk_mul_f32 v[100:101], v[64:65], v[100:101]
	v_pk_mul_f32 v[98:99], v[62:63], v[98:99]
	v_pk_mul_f32 v[102:103], v[60:61], v[102:103]
	v_mad_i64_i32 v[104:105], s[10:11], v114, s25, v[104:105]
	v_lshl_add_u64 v[104:105], v[184:185], 1, v[104:105]
	v_cvt_pk_bf16_f32 v98, v98, v99
	v_cvt_pk_bf16_f32 v99, v100, v101
	v_cvt_pk_bf16_f32 v100, v108, v109
	v_cvt_pk_bf16_f32 v101, v102, v103
	global_store_dwordx4 v[104:105], v[98:101], off

.LBB0_72:
	s_or_b64 exec, exec, s[10:11]
	s_nop 0
	v_readlane_b32 s6, v254, 35
	v_mov_b32_dpp v58, v54 row_ror:1 row_mask:0xf bank_mask:0xf
	v_mov_b32_dpp v59, v55 row_ror:1 row_mask:0xf bank_mask:0xf
	v_mov_b32_dpp v58, v38 row_shr:1 row_mask:0xf bank_mask:0xf
	v_mov_b32_dpp v59, v39 row_shr:1 row_mask:0xf bank_mask:0xf
	v_mov_b32_dpp v54, v22 row_ror:15 row_mask:0xf bank_mask:0xf
	v_mov_b32_dpp v55, v23 row_ror:15 row_mask:0xf bank_mask:0xf
	v_pk_fma_f32 v[58:59], v[82:83], v[58:59], v[94:95]
	v_mov_b32_dpp v54, v38 row_shl:1 row_mask:0xf bank_mask:0xf
	v_mov_b32_dpp v55, v39 row_shl:1 row_mask:0xf bank_mask:0xf
	v_pk_fma_f32 v[58:59], v[38:39], v[86:87], v[58:59]
	v_readlane_b32 s7, v254, 36
	v_pk_fma_f32 v[54:55], v[90:91], v[54:55], v[58:59]
	v_or_b32_e32 v60, 16, v114
	v_mul_f32_e32 v58, 0xbfb8aa3b, v54
	v_mul_f32_e32 v59, 0xbfb8aa3b, v55
	v_exp_f32_e32 v58, v58
	v_exp_f32_e32 v59, v59
	s_movk_i32 s10, 0x1600
	v_add_f32_e32 v58, 1.0, v58
	v_add_f32_e32 v59, 1.0, v59
	v_rcp_f32_e32 v58, v58
	v_rcp_f32_e32 v59, v59
	s_nop 0
	v_pk_mul_f32 v[54:55], v[54:55], v[58:59]
	s_nop 0
	v_pk_mul_f32 v[50:51], v[50:51], v[54:55]
	s_nop 0
	v_mov_b32_dpp v54, v56 row_ror:1 row_mask:0xf bank_mask:0xf
	v_mov_b32_dpp v55, v57 row_ror:1 row_mask:0xf bank_mask:0xf
	v_mov_b32_dpp v54, v40 row_shr:1 row_mask:0xf bank_mask:0xf
	v_mov_b32_dpp v55, v41 row_shr:1 row_mask:0xf bank_mask:0xf
	v_mov_b32_dpp v56, v24 row_ror:15 row_mask:0xf bank_mask:0xf
	v_mov_b32_dpp v57, v25 row_ror:15 row_mask:0xf bank_mask:0xf
	v_pk_fma_f32 v[54:55], v[84:85], v[54:55], v[96:97]
	v_mov_b32_dpp v56, v40 row_shl:1 row_mask:0xf bank_mask:0xf
	v_mov_b32_dpp v57, v41 row_shl:1 row_mask:0xf bank_mask:0xf
	v_pk_fma_f32 v[54:55], v[40:41], v[88:89], v[54:55]
	s_nop 0
	v_pk_fma_f32 v[54:55], v[92:93], v[56:57], v[54:55]
	s_nop 0
	v_mul_f32_e32 v56, 0xbfb8aa3b, v54
	v_mul_f32_e32 v57, 0xbfb8aa3b, v55
	v_exp_f32_e32 v56, v56
	v_exp_f32_e32 v57, v57
	v_add_f32_e32 v56, 1.0, v56
	v_add_f32_e32 v57, 1.0, v57
	v_rcp_f32_e32 v56, v56
	v_rcp_f32_e32 v57, v57
	s_nop 0
	v_pk_mul_f32 v[54:55], v[54:55], v[56:57]
	s_nop 0
	v_pk_mul_f32 v[52:53], v[52:53], v[54:55]
	s_nop 0
	v_mov_b32_dpp v54, v46 row_ror:1 row_mask:0xf bank_mask:0xf
	v_mov_b32_dpp v55, v47 row_ror:1 row_mask:0xf bank_mask:0xf
	v_mov_b32_dpp v54, v30 row_shr:1 row_mask:0xf bank_mask:0xf
	v_mov_b32_dpp v55, v31 row_shr:1 row_mask:0xf bank_mask:0xf
	v_mov_b32_dpp v46, v18 row_ror:15 row_mask:0xf bank_mask:0xf
	v_mov_b32_dpp v47, v19 row_ror:15 row_mask:0xf bank_mask:0xf
	v_pk_fma_f32 v[54:55], v[66:67], v[54:55], v[78:79]
	v_mov_b32_dpp v46, v30 row_shl:1 row_mask:0xf bank_mask:0xf
	v_mov_b32_dpp v47, v31 row_shl:1 row_mask:0xf bank_mask:0xf
	v_pk_fma_f32 v[54:55], v[30:31], v[70:71], v[54:55]
	s_nop 0
	v_pk_fma_f32 v[46:47], v[74:75], v[46:47], v[54:55]
	s_nop 0
	v_mul_f32_e32 v54, 0xbfb8aa3b, v46
	v_mul_f32_e32 v55, 0xbfb8aa3b, v47
	v_exp_f32_e32 v54, v54
	v_exp_f32_e32 v55, v55
	v_add_f32_e32 v54, 1.0, v54
	v_add_f32_e32 v55, 1.0, v55
	v_rcp_f32_e32 v54, v54
	v_rcp_f32_e32 v55, v55
	s_nop 0
	v_pk_mul_f32 v[46:47], v[46:47], v[54:55]
	s_nop 0
	v_pk_mul_f32 v[46:47], v[42:43], v[46:47]
	v_cvt_pk_bf16_f32 v46, v46, v47
	v_mov_b32_dpp v42, v48 row_ror:1 row_mask:0xf bank_mask:0xf
	v_mov_b32_dpp v43, v49 row_ror:1 row_mask:0xf bank_mask:0xf
	v_mov_b32_dpp v42, v32 row_shr:1 row_mask:0xf bank_mask:0xf
	v_mov_b32_dpp v43, v33 row_shr:1 row_mask:0xf bank_mask:0xf
	v_mov_b32_dpp v48, v20 row_ror:15 row_mask:0xf bank_mask:0xf
	v_mov_b32_dpp v49, v21 row_ror:15 row_mask:0xf bank_mask:0xf
	v_pk_fma_f32 v[42:43], v[68:69], v[42:43], v[80:81]
	v_mov_b32_dpp v48, v32 row_shl:1 row_mask:0xf bank_mask:0xf
	v_mov_b32_dpp v49, v33 row_shl:1 row_mask:0xf bank_mask:0xf
	v_pk_fma_f32 v[42:43], v[32:33], v[72:73], v[42:43]
	s_nop 0
	v_pk_fma_f32 v[42:43], v[76:77], v[48:49], v[42:43]
	s_nop 0
	v_mul_f32_e32 v48, 0xbfb8aa3b, v42
	v_mul_f32_e32 v49, 0xbfb8aa3b, v43
	v_exp_f32_e32 v48, v48
	v_exp_f32_e32 v49, v49
	v_add_f32_e32 v48, 1.0, v48
	v_add_f32_e32 v49, 1.0, v49
	v_rcp_f32_e32 v48, v48
	v_rcp_f32_e32 v49, v49
	s_nop 0
	v_pk_mul_f32 v[42:43], v[42:43], v[48:49]
	s_nop 0
	v_pk_mul_f32 v[48:49], v[44:45], v[42:43]
	v_mov_b64_e32 v[42:43], s[6:7]
	v_mad_i64_i32 v[44:45], s[6:7], v60, s10, v[42:43]
	v_lshl_add_u64 v[54:55], v[44:45], 0, v[138:139]
	v_cvt_pk_bf16_f32 v44, v50, v51
	v_cvt_pk_bf16_f32 v45, v52, v53
	v_cvt_pk_bf16_f32 v47, v48, v49
	global_store_dwordx4 v[54:55], v[44:47], off
	s_nop 1
	v_or_b32_e32 v46, 32, v114
	v_mov_b32_dpp v44, v38 row_ror:1 row_mask:0xf bank_mask:0xf
	v_mov_b32_dpp v45, v39 row_ror:1 row_mask:0xf bank_mask:0xf
	v_mov_b32_dpp v44, v22 row_shr:1 row_mask:0xf bank_mask:0xf
	v_mov_b32_dpp v45, v23 row_shr:1 row_mask:0xf bank_mask:0xf
	v_mov_b32_dpp v38, v6 row_ror:15 row_mask:0xf bank_mask:0xf
	v_mov_b32_dpp v39, v7 row_ror:15 row_mask:0xf bank_mask:0xf
	v_pk_fma_f32 v[44:45], v[82:83], v[44:45], v[94:95]
	v_mov_b32_dpp v38, v22 row_shl:1 row_mask:0xf bank_mask:0xf
	v_mov_b32_dpp v39, v23 row_shl:1 row_mask:0xf bank_mask:0xf
	v_pk_fma_f32 v[44:45], v[22:23], v[86:87], v[44:45]
	s_nop 0
	v_pk_fma_f32 v[38:39], v[90:91], v[38:39], v[44:45]
	s_nop 0
	v_mul_f32_e32 v44, 0xbfb8aa3b, v38
	v_mul_f32_e32 v45, 0xbfb8aa3b, v39
	v_exp_f32_e32 v44, v44
	v_exp_f32_e32 v45, v45
	v_add_f32_e32 v44, 1.0, v44
	v_add_f32_e32 v45, 1.0, v45
	v_rcp_f32_e32 v44, v44
	v_rcp_f32_e32 v45, v45
	s_nop 0
	v_pk_mul_f32 v[38:39], v[38:39], v[44:45]
	s_nop 0
	v_pk_mul_f32 v[34:35], v[34:35], v[38:39]
	s_nop 0
	v_mov_b32_dpp v38, v40 row_ror:1 row_mask:0xf bank_mask:0xf
	v_mov_b32_dpp v39, v41 row_ror:1 row_mask:0xf bank_mask:0xf
	v_mov_b32_dpp v38, v24 row_shr:1 row_mask:0xf bank_mask:0xf
	v_mov_b32_dpp v39, v25 row_shr:1 row_mask:0xf bank_mask:0xf
	v_mov_b32_dpp v40, v8 row_ror:15 row_mask:0xf bank_mask:0xf
	v_mov_b32_dpp v41, v9 row_ror:15 row_mask:0xf bank_mask:0xf
	v_pk_fma_f32 v[38:39], v[84:85], v[38:39], v[96:97]
	v_mov_b32_dpp v40, v24 row_shl:1 row_mask:0xf bank_mask:0xf
	v_mov_b32_dpp v41, v25 row_shl:1 row_mask:0xf bank_mask:0xf
	v_pk_fma_f32 v[38:39], v[24:25], v[88:89], v[38:39]
	s_nop 0
	v_pk_fma_f32 v[38:39], v[92:93], v[40:41], v[38:39]
	s_nop 0
	v_mul_f32_e32 v40, 0xbfb8aa3b, v38
	v_mul_f32_e32 v41, 0xbfb8aa3b, v39
	v_exp_f32_e32 v40, v40
	v_exp_f32_e32 v41, v41
	v_add_f32_e32 v40, 1.0, v40
	v_add_f32_e32 v41, 1.0, v41
	v_rcp_f32_e32 v40, v40
	v_rcp_f32_e32 v41, v41
	s_nop 0
	v_pk_mul_f32 v[38:39], v[38:39], v[40:41]
	s_nop 0
	v_pk_mul_f32 v[36:37], v[36:37], v[38:39]
	s_nop 0
	v_mov_b32_dpp v38, v30 row_ror:1 row_mask:0xf bank_mask:0xf
	v_mov_b32_dpp v39, v31 row_ror:1 row_mask:0xf bank_mask:0xf
	v_mov_b32_dpp v38, v18 row_shr:1 row_mask:0xf bank_mask:0xf
	v_mov_b32_dpp v39, v19 row_shr:1 row_mask:0xf bank_mask:0xf
	v_mov_b32_dpp v30, v2 row_ror:15 row_mask:0xf bank_mask:0xf
	v_mov_b32_dpp v31, v3 row_ror:15 row_mask:0xf bank_mask:0xf
	v_pk_fma_f32 v[38:39], v[66:67], v[38:39], v[78:79]
	v_mov_b32_dpp v30, v18 row_shl:1 row_mask:0xf bank_mask:0xf
	v_mov_b32_dpp v31, v19 row_shl:1 row_mask:0xf bank_mask:0xf
	v_pk_fma_f32 v[38:39], v[18:19], v[70:71], v[38:39]
	s_nop 0
	v_pk_fma_f32 v[30:31], v[74:75], v[30:31], v[38:39]
	s_nop 0
	v_mul_f32_e32 v38, 0xbfb8aa3b, v30
	v_mul_f32_e32 v39, 0xbfb8aa3b, v31
	v_exp_f32_e32 v38, v38
	v_exp_f32_e32 v39, v39
	v_add_f32_e32 v38, 1.0, v38
	v_add_f32_e32 v39, 1.0, v39
	v_rcp_f32_e32 v38, v38
	v_rcp_f32_e32 v39, v39
	s_nop 0
	v_pk_mul_f32 v[30:31], v[30:31], v[38:39]
	s_nop 0
	v_pk_mul_f32 v[30:31], v[26:27], v[30:31]
	s_nop 0
	v_mov_b32_dpp v26, v32 row_ror:1 row_mask:0xf bank_mask:0xf
	v_mov_b32_dpp v27, v33 row_ror:1 row_mask:0xf bank_mask:0xf
	v_mov_b32_dpp v26, v20 row_shr:1 row_mask:0xf bank_mask:0xf
	v_mov_b32_dpp v27, v21 row_shr:1 row_mask:0xf bank_mask:0xf
	v_mov_b32_dpp v32, v4 row_ror:15 row_mask:0xf bank_mask:0xf
	v_mov_b32_dpp v33, v5 row_ror:15 row_mask:0xf bank_mask:0xf
	v_pk_fma_f32 v[26:27], v[68:69], v[26:27], v[80:81]
	v_mov_b32_dpp v32, v20 row_shl:1 row_mask:0xf bank_mask:0xf
	v_mov_b32_dpp v33, v21 row_shl:1 row_mask:0xf bank_mask:0xf
	v_pk_fma_f32 v[26:27], v[20:21], v[72:73], v[26:27]
	s_nop 0
	v_pk_fma_f32 v[26:27], v[76:77], v[32:33], v[26:27]
	s_nop 0
	v_mul_f32_e32 v32, 0xbfb8aa3b, v26
	v_mul_f32_e32 v33, 0xbfb8aa3b, v27
	v_exp_f32_e32 v32, v32
	v_exp_f32_e32 v33, v33
	v_add_f32_e32 v32, 1.0, v32
	v_add_f32_e32 v33, 1.0, v33
	v_rcp_f32_e32 v32, v32
	v_rcp_f32_e32 v33, v33
	s_nop 0
	v_pk_mul_f32 v[26:27], v[26:27], v[32:33]
	s_nop 0
	v_pk_mul_f32 v[32:33], v[28:29], v[26:27]
	v_mad_i64_i32 v[26:27], s[6:7], v46, s10, v[42:43]
	v_cvt_pk_bf16_f32 v28, v30, v31
	v_lshl_add_u64 v[38:39], v[26:27], 0, v[138:139]
	v_cvt_pk_bf16_f32 v26, v34, v35
	v_cvt_pk_bf16_f32 v27, v36, v37
	v_cvt_pk_bf16_f32 v29, v32, v33
	v_mov_b32_dpp v30, v22 row_ror:1 row_mask:0xf bank_mask:0xf
	v_mov_b32_dpp v31, v23 row_ror:1 row_mask:0xf bank_mask:0xf
	global_store_dwordx4 v[38:39], v[26:29], off
	v_mov_b32_dpp v22, v18 row_ror:1 row_mask:0xf bank_mask:0xf
	v_mov_b32_dpp v23, v19 row_ror:1 row_mask:0xf bank_mask:0xf
	v_mov_b32_e32 v32, v1
	v_mov_b32_e32 v33, v1
	v_mov_b32_dpp v26, v24 row_ror:1 row_mask:0xf bank_mask:0xf
	v_mov_b32_e32 v28, v1
	v_mov_b32_dpp v27, v25 row_ror:1 row_mask:0xf bank_mask:0xf
	v_mov_b32_e32 v29, v1
	v_mov_b32_e32 v24, v1
	v_mov_b32_e32 v25, v1
	v_mov_b32_dpp v18, v20 row_ror:1 row_mask:0xf bank_mask:0xf
	v_mov_b32_e32 v20, v1
	v_mov_b32_dpp v19, v21 row_ror:1 row_mask:0xf bank_mask:0xf
	v_mov_b32_e32 v21, v1
	v_mov_b32_dpp v30, v6 row_shr:1 row_mask:0xf bank_mask:0xf
	v_mov_b32_dpp v32, v6 row_shl:1 row_mask:0xf bank_mask:0xf
	v_mov_b32_dpp v31, v7 row_shr:1 row_mask:0xf bank_mask:0xf
	v_mov_b32_dpp v33, v7 row_shl:1 row_mask:0xf bank_mask:0xf
	v_mov_b32_dpp v26, v8 row_shr:1 row_mask:0xf bank_mask:0xf
	v_mov_b32_dpp v28, v8 row_shl:1 row_mask:0xf bank_mask:0xf
	v_mov_b32_dpp v27, v9 row_shr:1 row_mask:0xf bank_mask:0xf
	v_mov_b32_dpp v29, v9 row_shl:1 row_mask:0xf bank_mask:0xf
	v_mov_b32_dpp v22, v2 row_shr:1 row_mask:0xf bank_mask:0xf
	v_mov_b32_dpp v24, v2 row_shl:1 row_mask:0xf bank_mask:0xf
	v_mov_b32_dpp v23, v3 row_shr:1 row_mask:0xf bank_mask:0xf
	v_mov_b32_dpp v25, v3 row_shl:1 row_mask:0xf bank_mask:0xf
	v_mov_b32_dpp v18, v4 row_shr:1 row_mask:0xf bank_mask:0xf
	v_mov_b32_dpp v20, v4 row_shl:1 row_mask:0xf bank_mask:0xf
	v_mov_b32_dpp v19, v5 row_shr:1 row_mask:0xf bank_mask:0xf
	v_mov_b32_dpp v21, v5 row_shl:1 row_mask:0xf bank_mask:0xf
	s_and_saveexec_b64 s[6:7], s[14:15]
	s_cbranch_execz .LBB0_74
	v_pk_fma_f32 v[26:27], v[84:85], v[26:27], v[96:97]
	v_pk_fma_f32 v[22:23], v[66:67], v[22:23], v[78:79]
	v_pk_fma_f32 v[26:27], v[8:9], v[88:89], v[26:27]
	v_pk_fma_f32 v[18:19], v[68:69], v[18:19], v[80:81]
	v_pk_fma_f32 v[26:27], v[92:93], v[28:29], v[26:27]
	v_pk_fma_f32 v[30:31], v[82:83], v[30:31], v[94:95]
	v_mul_f32_e32 v28, 0xbfb8aa3b, v26
	v_mul_f32_e32 v29, 0xbfb8aa3b, v27
	v_exp_f32_e32 v28, v28
	v_exp_f32_e32 v29, v29
	v_pk_fma_f32 v[22:23], v[2:3], v[70:71], v[22:23]
	v_pk_fma_f32 v[18:19], v[4:5], v[72:73], v[18:19]
	v_add_f32_e32 v28, 1.0, v28
	v_add_f32_e32 v29, 1.0, v29
	v_rcp_f32_e32 v28, v28
	v_rcp_f32_e32 v29, v29
	v_pk_fma_f32 v[30:31], v[6:7], v[86:87], v[30:31]
	v_pk_fma_f32 v[22:23], v[74:75], v[24:25], v[22:23]
	v_pk_fma_f32 v[18:19], v[76:77], v[20:21], v[18:19]
	v_pk_fma_f32 v[30:31], v[90:91], v[32:33], v[30:31]
	v_mul_f32_e32 v24, 0xbfb8aa3b, v22
	v_mul_f32_e32 v20, 0xbfb8aa3b, v18
	v_mul_f32_e32 v21, 0xbfb8aa3b, v19
	v_mul_f32_e32 v32, 0xbfb8aa3b, v30
	v_mul_f32_e32 v33, 0xbfb8aa3b, v31
	v_pk_mul_f32 v[26:27], v[26:27], v[28:29]
	v_exp_f32_e32 v28, v24
	v_mul_f32_e32 v24, 0xbfb8aa3b, v23
	v_exp_f32_e32 v20, v20
	v_exp_f32_e32 v21, v21
	v_exp_f32_e32 v32, v32
	v_exp_f32_e32 v33, v33
	v_exp_f32_e32 v29, v24
	v_add_f32_e32 v20, 1.0, v20
	v_add_f32_e32 v21, 1.0, v21
	v_add_f32_e32 v32, 1.0, v32
	v_add_f32_e32 v33, 1.0, v33
	v_pk_mul_f32 v[24:25], v[16:17], v[26:27]
	v_add_f32_e32 v26, 1.0, v28
	v_add_f32_e32 v27, 1.0, v29
	v_rcp_f32_e32 v20, v20
	v_rcp_f32_e32 v21, v21
	v_rcp_f32_e32 v32, v32
	v_rcp_f32_e32 v33, v33
	v_rcp_f32_e32 v26, v26
	v_rcp_f32_e32 v27, v27
	v_readlane_b32 s10, v254, 35
	v_pk_mul_f32 v[18:19], v[18:19], v[20:21]
	v_readlane_b32 s11, v254, 36
	v_pk_mul_f32 v[30:31], v[30:31], v[32:33]
	v_pk_mul_f32 v[22:23], v[22:23], v[26:27]
	v_or_b32_e32 v28, 48, v114
	v_pk_mul_f32 v[26:27], v[12:13], v[18:19]
	v_mov_b64_e32 v[18:19], s[10:11]
	s_movk_i32 s10, 0x1600
	v_pk_mul_f32 v[30:31], v[14:15], v[30:31]
	v_pk_mul_f32 v[22:23], v[10:11], v[22:23]
	v_mad_i64_i32 v[18:19], s[10:11], v28, s10, v[18:19]
	v_lshl_add_u64 v[28:29], v[184:185], 1, v[18:19]
	v_cvt_pk_bf16_f32 v18, v30, v31
	v_cvt_pk_bf16_f32 v19, v24, v25
	v_cvt_pk_bf16_f32 v20, v22, v23
	v_cvt_pk_bf16_f32 v21, v26, v27
	global_store_dwordx4 v[28:29], v[18:21], off
